# v78 + stale vmcnt terms dropped from the first-tile QK waits (Q loads already drained by vmcnt(4)), wait after DMA(2) counted, type-0 DMA(1) wait moved to its barrier
# baseline (speedup 1.0000x reference)
; #define SBAR() __builtin_amdgcn_sched_barrier(0)
; __device__ __forceinline__ int v_rd_base(int lane) { return ((lane & 3) << 3) | (((lane >> 2) & 3) << 6) | (((lane >> 4) & 1) << 5) | (((lane >> 5) & 1) << 8); }
; #define DMAV(t, b) do { DMA1(t, b, 2); DMA1(t, b, 3); } while (0)
; #define LANDED() do { asm volatile("s_waitcnt vmcnt(0)" ::: "memory"); __syncthreads(); } while (0)
; #define BLK_X(N0, N1, P0, P1, alP, t) do { SBAR(); __builtin_amdgcn_s_setprio(1); qkt(N0, N1, KBUF((t) & 3), qr, r32, hi, mapB); \
;     if constexpr (!SH) v_frag_read<0>(vfa, VBUF(((t) - 1) & 3)); \
;     finishSM<SH>(P0, P1, alP, l_reg, pa0, pa1, pa2, pa3); __builtin_amdgcn_s_setprio(0); SBAR(); } while (0)
; template <bool SH> __device__ __forceinline__ void attn_unit(bf16_t* __restrict__ proj, int tok0, int kv0, int seq, int h, float lam, float oscale, const float* __restrict__ subg, char* lds, bool dry) {
;     ...
;   const bf16_t* Qw = proj + (size_t)(tok0 + wq * 32 + r32) * NPROJ + C_Q + h * 128 + mp * 64 + hi * 8;
; #pragma unroll
;   for (int d0 = 0; d0 < 4; ++d0) qr[d0] = *reinterpret_cast<const bf16x8*>(Qw + d0 * 16);
;   unsigned vk0, vv0;
;   { const int c = tid;
;     { const int row = c >> 4, pc = c & 15, scn = pc ^ (row & 7); vk0 = (unsigned)(row * LDK + scn * 8) * 2u; }
;     { const int sub = c >> 5, kk = (sub >> 2) * 8 + ((c >> 2) & 7), col = (sub & 3) * 32 + (c & 3) * 8; vv0 = (unsigned)(kk * LDK + col) * 2u; } }
;   const unsigned ldsb = (unsigned)(uintptr_t)ldsl;
;   const int vbb = (int)(uintptr_t)ldsl + 16384 + v_rd_base(lane);
;     ...
;   DMA(0, 0); LANDED();
;   DMA(1, 1);
;   if (ty == 0) {
;     qkt(pA0, pA1, KBUF(0), qr, r32, hi, mapB); partialSM<SH>(pA0, pA1, m_reg, mnA, alA);
;     LANDED();
;     for (int j = 1; j + 1 < NT; j += 2) {
;       BLK_X(pB0, pB1, pA0, pA1, alA, j); DMAV(j + 1, (j + 1) & 3); BLK_Y(pB0, pB1, mnB, alB, j - 1); LANDED();
;       BLK_X(pA0, pA1, pB0, pB1, alB, j + 1); DMAV(j + 2, (j + 2) & 3); BLK_Y(pA0, pA1, mnA, alA, j); LANDED();
;     }
;     BLK_X(pB0, pB1, pA0, pA1, alA, NT - 1); BLK_Y(pB0, pB1, mnB, alB, NT - 2);
;     finishSM<SH>(pB0, pB1, alB, l_reg, pa0, pa1, pa2, pa3); SBAR();
;     if constexpr (SH) pv_d0(o, VBUF((NT - 1) & 3), pa0, pa1, pa2, pa3); else pv_d0_pipe<false>(o, VBUF((NT - 1) & 3), pa0, pa1, pa2, pa3, vfa);
;   } else {
;     qkt(pA0, pA1, KBUF(0), qr, r32, hi, mapB);
;     LANDED();
.LBB0_353:
	v_mov_b32_e32 v182, v184
	s_mov_b32 s59, s81
	v_readfirstlane_b32 s14, v182
	s_ashr_i32 s17, s14, 6
	s_and_b32 s15, s17, 3
	s_ashr_i32 s16, s14, 8
	s_lshl_b64 s[6:7], s[58:59], 1
	s_add_u32 s8, s68, s6
	s_addc_u32 s9, s69, s7
	s_lshl_b32 s0, s15, 5
	v_and_b32_e32 v205, 31, v182
	s_add_i32 s0, s0, s3
	v_add_u32_e32 v2, s0, v205
	v_mov_b64_e32 v[0:1], s[68:69]
	v_mad_i64_i32 v[0:1], s[0:1], v2, s25, v[0:1]
	s_lshl_b32 s4, s96, 1
	s_mov_b32 s5, s81
	s_lshl_b32 s0, s16, 6
	v_bfe_u32 v204, v182, 5, 1
	v_lshl_add_u64 v[0:1], v[0:1], 0, s[4:5]
	s_ashr_i32 s1, s0, 31
	v_lshl_add_u64 v[0:1], s[0:1], 1, v[0:1]
	v_lshlrev_b32_e32 v252, 4, v204
	v_lshl_add_u64 v[0:1], v[0:1], 0, v[252:253]
	global_load_dwordx4 v[140:143], v[0:1], off offset:3072
	global_load_dwordx4 v[136:139], v[0:1], off offset:3104
	global_load_dwordx4 v[132:135], v[0:1], off offset:3136
	global_load_dwordx4 v[128:131], v[0:1], off offset:3168
	s_add_u32 s20, s8, s4
	s_addc_u32 s21, s9, 0
	s_add_u32 s10, s20, 0x1000
	v_ashrrev_i32_e32 v0, 4, v182
	v_and_b32_e32 v1, 15, v182
	s_addc_u32 s11, s21, 0
	v_bitop3_b32 v1, v0, v1, 15 bitop3:0x6c
	v_mul_lo_u32 v2, v0, s25
	v_ashrrev_i32_e32 v183, 2, v182
	s_add_u32 s8, s20, 0x1400
	v_lshl_or_b32 v166, v1, 4, v2
	v_and_b32_e32 v1, 7, v183
	s_mov_b32 s0, 0x3ffff8
	s_addc_u32 s9, s21, 0
	v_and_or_b32 v0, v0, s0, v1
	v_and_b32_e32 v202, 3, v182
	s_add_i32 s18, 0, 0x4000
	v_and_b32_e32 v1, 0x60, v182
	v_lshlrev_b32_e32 v2, 3, v202
	v_mul_u32_u24_e32 v0, 0xc00, v0
	s_add_u32 s0, s20, 0x31000
	v_and_b32_e32 v203, 63, v182
	v_or3_b32 v0, v2, v1, v0
	v_lshlrev_b32_e32 v1, 4, v182
	s_addc_u32 s1, s21, 0
	v_lshlrev_b32_e32 v207, 1, v0
	v_lshlrev_b32_e32 v0, 3, v203
	v_and_b32_e32 v1, 0xc0, v1
	v_lshlrev_b32_e32 v2, 1, v182
	s_add_u32 s12, s20, 0x31400
	v_and_or_b32 v1, v0, 24, v1
	v_and_b32_e32 v2, 32, v2
	v_and_b32_e32 v0, 0x100, v0
	s_addc_u32 s13, s21, 0
	s_lshl_b32 s17, s17, 10
	v_or3_b32 v206, v1, v2, v0
	s_add_i32 s5, s17, 0
	v_add_u32_e32 v208, s18, v206
	s_add_i32 s19, s5, 0x2000
	s_add_i32 s18, s17, s18
	s_add_i32 s26, s5, 0x6000
	s_mov_b32 s27, m0
	s_mov_b32 m0, s5
	s_nop 0
	global_load_lds_dwordx4 v166, s[10:11]
	s_mov_b32 m0, s19
	s_nop 0
	global_load_lds_dwordx4 v166, s[0:1]
	s_mov_b32 m0, s18
	s_nop 0
	global_load_lds_dwordx4 v207, s[8:9]
	s_mov_b32 m0, s26
	s_nop 0
	global_load_lds_dwordx4 v207, s[12:13]
	s_mov_b32 m0, s27
	s_add_u32 s0, s20, 0x61000
	s_addc_u32 s1, s21, 0
	s_add_u32 s12, s20, 0x61400
	s_addc_u32 s13, s21, 0
	s_add_u32 s18, s20, 0x91000
	s_addc_u32 s19, s21, 0
	s_add_u32 s20, s20, 0x91400
	s_addc_u32 s21, s21, 0
	s_add_i32 s26, s5, 0x8000
	s_add_i32 s27, s5, 0xa000
	s_add_i32 s58, s5, 0xc000
	s_add_i32 s59, s5, 0xe000
	s_mov_b32 s60, m0
	s_mov_b32 m0, s26
	s_nop 0
	global_load_lds_dwordx4 v166, s[0:1]
	s_mov_b32 m0, s27
	s_nop 0
	global_load_lds_dwordx4 v166, s[18:19]
	s_mov_b32 m0, s58
	s_nop 0
	global_load_lds_dwordx4 v207, s[12:13]
	s_mov_b32 m0, s59
	s_nop 0
	global_load_lds_dwordx4 v207, s[20:21]
	s_mov_b32 m0, s60
	s_waitcnt vmcnt(4)
	s_barrier
	s_cmpk_lt_u32 s14, 0x100
	s_cselect_b64 s[0:1], -1, 0
	s_cmpk_gt_u32 s14, 0xff
	s_mov_b64 s[12:13], -1
	v_lshlrev_b32_e32 v209, 8, v205
	v_lshlrev_b32_e32 v210, 4, v205
	s_cbranch_scc0 .LBB0_357
	s_lshl_b32 s12, s16, 7
	v_and_b32_e32 v41, 0xf0, v210
	v_bitop3_b32 v167, s12, v41, v252 bitop3:0x36
	v_add_u32_e32 v165, v167, v209
	v_add_u32_e32 v42, 0, v165
	ds_read_b128 v[0:3], v42
	ds_read_b128 v[16:19], v42 offset:8192
	v_or_b32_e32 v40, s12, v252
	v_bitop3_b32 v168, v40, v41, 32 bitop3:0x36
	s_waitcnt lgkmcnt(1)
	v_mfma_f32_32x32x16_bf16 v[0:15], v[0:3], v[140:143], 0
	v_add_u32_e32 v164, v168, v209
	v_add_u32_e32 v43, 0, v164
	ds_read_b128 v[32:35], v43
	ds_read_b128 v[36:39], v43 offset:8192
	v_bitop3_b32 v169, v40, v41, 64 bitop3:0x36
	v_add_u32_e32 v163, v169, v209
	v_add_u32_e32 v44, 0, v163
	s_movk_i32 s12, 0x60
	s_waitcnt lgkmcnt(2)
	v_mfma_f32_32x32x16_bf16 v[16:31], v[16:19], v[140:143], 0
	v_bitop3_b32 v170, v40, v41, s12 bitop3:0x36
	v_add_u32_e32 v162, v170, v209
	v_add_u32_e32 v40, 0, v162
	s_add_u32 s12, s10, 0xc0000
	s_addc_u32 s13, s11, 0
	s_add_u32 s20, s8, 0xc0000
	s_addc_u32 s21, s9, 0
	s_waitcnt lgkmcnt(1)
	v_mfma_f32_32x32x16_bf16 v[0:15], v[32:35], v[136:139], v[0:15]
	s_add_u32 s26, s10, 0xf0000
	s_addc_u32 s27, s11, 0
	s_add_u32 s58, s8, 0xf0000
	s_addc_u32 s59, s9, 0
	s_add_i32 s19, s5, 0x10000
	s_add_i32 s60, s5, 0x12000
	s_add_i32 s61, s5, 0x14000
	s_waitcnt lgkmcnt(0)
	v_mfma_f32_32x32x16_bf16 v[16:31], v[36:39], v[136:139], v[16:31]
	ds_read_b128 v[32:35], v44
	ds_read_b128 v[36:39], v44 offset:8192
	s_add_i32 s64, s5, 0x16000
	s_mov_b32 s18, 4
	s_waitcnt lgkmcnt(1)
	v_mfma_f32_32x32x16_bf16 v[0:15], v[32:35], v[132:135], v[0:15]
	s_waitcnt lgkmcnt(0)
	v_mfma_f32_32x32x16_bf16 v[16:31], v[36:39], v[132:135], v[16:31]
	ds_read_b128 v[32:35], v40
	ds_read_b128 v[36:39], v40 offset:8192
	s_waitcnt vmcnt(0)
	s_waitcnt lgkmcnt(0)
	s_barrier
; #define PK4(P, BASE, OUT) do { u32x4 w = {cvtpk_b(P[BASE + 0], P[BASE + 1]), cvtpk_b(P[BASE + 2], P[BASE + 3]), cvtpk_b(P[BASE + 4], P[BASE + 5]), cvtpk_b(P[BASE + 6], P[BASE + 7])}; \
;     OUT = *reinterpret_cast<bf16x8*>(&w); } while (0)
; #define LANDED() do { asm volatile("s_waitcnt vmcnt(0)" ::: "memory"); __syncthreads(); } while (0)
; #define BLK_X(N0, N1, P0, P1, alP, t) do { SBAR(); __builtin_amdgcn_s_setprio(1); qkt(N0, N1, KBUF((t) & 3), qr, r32, hi, mapB); \
;     if constexpr (!SH) v_frag_read<0>(vfa, VBUF(((t) - 1) & 3)); \
;     finishSM<SH>(P0, P1, alP, l_reg, pa0, pa1, pa2, pa3); __builtin_amdgcn_s_setprio(0); SBAR(); } while (0)
; template <bool SH> __device__ __forceinline__ void finishSM(f32x16& p0, f32x16& p1, float alpha, float& l_reg, bf16x8& pa0, bf16x8& pa1, bf16x8& pa2, bf16x8& pa3) {
;   if constexpr (!SH) {
; #pragma unroll
;     for (int r = 0; r < 16; ++r) { p0[r] = __builtin_amdgcn_exp2f(p0[r]); p1[r] = __builtin_amdgcn_exp2f(p1[r]); }
;   }
;   float ps = 0;
; #pragma unroll
;   for (int r = 0; r < 16; ++r) ps += p0[r];
; #pragma unroll
;   for (int r = 0; r < 16; ++r) ps += p1[r];
;   if constexpr (SH) l_reg = l_reg * alpha + ps; else l_reg += ps;
;     ...
;   PK4(p0, 0, pa0); PK4(p0, 8, pa1); PK4(p1, 0, pa2); PK4(p1, 8, pa3);
;     ...
; }
; __device__ __forceinline__ void qkt(f32x16& p0, f32x16& p1, const char* Ks, const bf16x8* qr, int r32, int hi, int mapB) {
;   p0 = f32x16{}; p1 = f32x16{};
; #pragma unroll
;   for (int d0 = 0; d0 < 4; ++d0) { const int cb = (d0 * 16 + hi * 8) * 2 + mapB;
;     bf16x8 b0 = *reinterpret_cast<const bf16x8*>(Ks + KSWZ(r32, cb));
;     bf16x8 b1 = *reinterpret_cast<const bf16x8*>(Ks + KSWZ(32 + r32, cb));
;     p0 = __builtin_amdgcn_mfma_f32_32x32x16_bf16(b0, qr[d0], p0, 0, 0, 0);
;     p1 = __builtin_amdgcn_mfma_f32_32x32x16_bf16(b1, qr[d0], p1, 0, 0, 0); }
; }
; template <bool SH> __device__ __forceinline__ void attn_unit(bf16_t* __restrict__ proj, int tok0, int kv0, int seq, int h, float lam, float oscale, const float* __restrict__ subg, char* lds, bool dry) {
;     ...
;     qkt(pA0, pA1, KBUF(0), qr, r32, hi, mapB);
;     LANDED();
;     DMA(2, 2); DMA1X(2, 2, 0, wid - 4); DMA1X(2, 2, 1, wid - 4); partialSM<SH>(pA0, pA1, m_reg, mnA, alA); BLK_X(pB0, pB1, pA0, pA1, alA, 1); LANDED();
	s_mov_b32 s65, m0
	s_mov_b32 m0, s19
	s_nop 0
	global_load_lds_dwordx4 v166, s[12:13]
	s_mov_b32 m0, s60
	s_nop 0
	global_load_lds_dwordx4 v166, s[26:27]
	s_mov_b32 m0, s61
	s_nop 0
	global_load_lds_dwordx4 v207, s[20:21]
	s_mov_b32 m0, s64
	s_nop 0
	global_load_lds_dwordx4 v207, s[58:59]
	s_mov_b32 m0, s65
	s_add_u32 s12, s10, 0xa8000
	s_waitcnt vmcnt(4)
	v_mfma_f32_32x32x16_bf16 v[0:15], v[32:35], v[128:131], v[0:15]
	s_addc_u32 s13, s11, 0
	s_add_i32 s19, s17, 0xfffff000
	s_add_i32 s20, s5, 0xf000
	s_setprio 3
	s_mov_b32 s21, m0
	s_mov_b32 m0, s20
	s_nop 0
	global_load_lds_dwordx4 v166, s[12:13]
	s_mov_b32 m0, s21
	s_setprio 0
	s_add_u32 s12, s10, 0xd8000
	s_addc_u32 s13, s11, 0
	s_add_i32 s20, s5, 0x11000
	v_mfma_f32_32x32x16_bf16 v[16:31], v[36:39], v[128:131], v[16:31]
	s_setprio 3
	s_mov_b32 s21, m0
	s_mov_b32 m0, s20
	s_nop 0
	global_load_lds_dwordx4 v166, s[12:13]
	s_mov_b32 m0, s21
	s_setprio 0
	s_setprio 1
	ds_read_b128 v[32:35], v42 offset:32768
	ds_read_b128 v[36:39], v42 offset:40960
	s_waitcnt lgkmcnt(1)
	v_mfma_f32_32x32x16_bf16 v[64:79], v[32:35], v[140:143], 0
	s_waitcnt lgkmcnt(0)
	v_mfma_f32_32x32x16_bf16 v[80:95], v[36:39], v[140:143], 0
	ds_read_b128 v[32:35], v43 offset:32768
	ds_read_b128 v[36:39], v43 offset:40960
	s_waitcnt lgkmcnt(1)
	v_mfma_f32_32x32x16_bf16 v[64:79], v[32:35], v[136:139], v[64:79]
	s_waitcnt lgkmcnt(0)
	v_mfma_f32_32x32x16_bf16 v[80:95], v[36:39], v[136:139], v[80:95]
	ds_read_b128 v[32:35], v44 offset:32768
	ds_read_b128 v[36:39], v44 offset:40960
	s_waitcnt lgkmcnt(1)
	v_mfma_f32_32x32x16_bf16 v[64:79], v[32:35], v[132:135], v[64:79]
	s_waitcnt lgkmcnt(0)
	v_mfma_f32_32x32x16_bf16 v[80:95], v[36:39], v[132:135], v[80:95]
	ds_read_b128 v[32:35], v40 offset:32768
	ds_read_b128 v[36:39], v40 offset:40960
	ds_read_b64_tr_b16 v[156:157], v208 offset:0
	ds_read_b64_tr_b16 v[158:159], v208 offset:0x800
	ds_read_b64_tr_b16 v[152:153], v208 offset:0x1000
	ds_read_b64_tr_b16 v[154:155], v208 offset:0x1800
	ds_read_b64_tr_b16 v[148:149], v208 offset:0x2000
	ds_read_b64_tr_b16 v[150:151], v208 offset:0x2800
	s_waitcnt lgkmcnt(1)
	v_mfma_f32_32x32x16_bf16 v[64:79], v[32:35], v[128:131], v[64:79]
	ds_read_b64_tr_b16 v[144:145], v208 offset:0x3000
	ds_read_b64_tr_b16 v[146:147], v208 offset:0x3800
	s_waitcnt lgkmcnt(0)
	v_mfma_f32_32x32x16_bf16 v[80:95], v[36:39], v[128:131], v[80:95]
	s_setprio 0
	v_exp_f32_e32 v0, v0
	v_exp_f32_e32 v1, v1
	v_exp_f32_e32 v2, v2
	v_exp_f32_e32 v3, v3
	v_exp_f32_e32 v4, v4
	v_add_f32_e32 v32, 0, v0
	v_exp_f32_e32 v5, v5
	v_add_f32_e32 v32, v1, v32
	v_exp_f32_e32 v6, v6
	v_add_f32_e32 v32, v2, v32
	v_exp_f32_e32 v7, v7
	v_add_f32_e32 v32, v3, v32
	v_exp_f32_e32 v8, v8
	v_add_f32_e32 v32, v4, v32
	v_exp_f32_e32 v9, v9
	v_add_f32_e32 v32, v5, v32
	v_exp_f32_e32 v10, v10
	v_add_f32_e32 v32, v6, v32
	v_exp_f32_e32 v11, v11
	v_add_f32_e32 v32, v7, v32
	v_exp_f32_e32 v12, v12
	v_add_f32_e32 v32, v8, v32
	v_exp_f32_e32 v13, v13
	v_add_f32_e32 v32, v9, v32
	v_exp_f32_e32 v14, v14
	v_add_f32_e32 v32, v10, v32
	v_exp_f32_e32 v15, v15
	v_add_f32_e32 v32, v11, v32
	v_exp_f32_e32 v16, v16
	v_add_f32_e32 v32, v12, v32
	v_exp_f32_e32 v17, v17
	v_add_f32_e32 v32, v13, v32
	v_exp_f32_e32 v18, v18
	v_add_f32_e32 v32, v14, v32
	v_exp_f32_e32 v19, v19
	v_add_f32_e32 v32, v15, v32
	v_exp_f32_e32 v20, v20
	v_add_f32_e32 v32, v16, v32
	v_exp_f32_e32 v21, v21
	v_add_f32_e32 v32, v17, v32
	v_exp_f32_e32 v22, v22
	v_add_f32_e32 v32, v18, v32
	v_exp_f32_e32 v23, v23
	v_add_f32_e32 v32, v19, v32
	v_exp_f32_e32 v24, v24
	v_add_f32_e32 v32, v20, v32
	v_exp_f32_e32 v25, v25
	v_add_f32_e32 v32, v21, v32
	v_exp_f32_e32 v26, v26
	v_add_f32_e32 v32, v22, v32
	v_exp_f32_e32 v27, v27
	v_add_f32_e32 v32, v23, v32
	v_exp_f32_e32 v28, v28
	v_add_f32_e32 v32, v24, v32
	v_exp_f32_e32 v29, v29
	v_add_f32_e32 v32, v25, v32
	v_exp_f32_e32 v30, v30
	v_add_f32_e32 v32, v26, v32
	v_exp_f32_e32 v31, v31
	v_add_f32_e32 v32, v27, v32
	v_add_f32_e32 v32, v28, v32
	v_add_f32_e32 v32, v29, v32
	s_add_u32 s12, s80, s6
	s_waitcnt vmcnt(0)
	v_add_f32_e32 v32, v30, v32
	s_addc_u32 s13, 0, s7
	v_readlane_b32 s20, v255, 6
	v_add_f32_e32 v32, v31, v32
	s_add_u32 s12, s20, s12
	v_readlane_b32 s20, v255, 8
	v_mov_b32_e32 v48, 0
	v_add_f32_e32 v171, 0, v32
	v_cvt_pk_bf16_f32 v108, v0, v1
	v_cvt_pk_bf16_f32 v109, v2, v3
	v_cvt_pk_bf16_f32 v110, v4, v5
	v_cvt_pk_bf16_f32 v111, v6, v7
	v_cvt_pk_bf16_f32 v104, v8, v9
	v_cvt_pk_bf16_f32 v105, v10, v11
	v_cvt_pk_bf16_f32 v106, v12, v13
	v_cvt_pk_bf16_f32 v107, v14, v15
	v_cvt_pk_bf16_f32 v100, v16, v17
	v_cvt_pk_bf16_f32 v101, v18, v19
	v_cvt_pk_bf16_f32 v102, v20, v21
	v_cvt_pk_bf16_f32 v103, v22, v23
	v_cvt_pk_bf16_f32 v96, v24, v25
	v_cvt_pk_bf16_f32 v97, v26, v27
	v_cvt_pk_bf16_f32 v98, v28, v29
	v_cvt_pk_bf16_f32 v99, v30, v31
	s_addc_u32 s13, s20, s13
	s_mov_b32 s20, 0x18000
	v_mov_b32_e32 v49, v48
	v_mov_b32_e32 v50, v48
	v_mov_b32_e32 v51, v48
	v_mov_b32_e32 v52, v48
	v_mov_b32_e32 v53, v48
	v_mov_b32_e32 v54, v48
	v_mov_b32_e32 v55, v48
	v_mov_b32_e32 v56, v48
	v_mov_b32_e32 v57, v48
	v_mov_b32_e32 v58, v48
	v_mov_b32_e32 v59, v48
	v_mov_b32_e32 v60, v48
	v_mov_b32_e32 v61, v48
	v_mov_b32_e32 v62, v48
	v_mov_b32_e32 v63, v48
	v_mov_b32_e32 v32, v48
	v_mov_b32_e32 v33, v48
	v_mov_b32_e32 v34, v48
	v_mov_b32_e32 v35, v48
	v_mov_b32_e32 v36, v48
	v_mov_b32_e32 v37, v48
	v_mov_b32_e32 v38, v48
	v_mov_b32_e32 v39, v48
	v_mov_b32_e32 v40, v48
	v_mov_b32_e32 v41, v48
	v_mov_b32_e32 v42, v48
	v_mov_b32_e32 v43, v48
	v_mov_b32_e32 v44, v48
	v_mov_b32_e32 v45, v48
	v_mov_b32_e32 v46, v48
	v_mov_b32_e32 v47, v48
	v_mov_b32_e32 v16, v48
	v_mov_b32_e32 v17, v48
	v_mov_b32_e32 v18, v48
	v_mov_b32_e32 v19, v48
	v_mov_b32_e32 v20, v48
	v_mov_b32_e32 v21, v48
	v_mov_b32_e32 v22, v48
	v_mov_b32_e32 v23, v48
	v_mov_b32_e32 v24, v48
	v_mov_b32_e32 v25, v48
	v_mov_b32_e32 v26, v48
	v_mov_b32_e32 v27, v48
	v_mov_b32_e32 v28, v48
	v_mov_b32_e32 v29, v48
	v_mov_b32_e32 v30, v48
	v_mov_b32_e32 v31, v48
	v_mov_b32_e32 v0, v48
	v_mov_b32_e32 v1, v48
	v_mov_b32_e32 v2, v48
	v_mov_b32_e32 v3, v48
	v_mov_b32_e32 v4, v48
	v_mov_b32_e32 v5, v48
	v_mov_b32_e32 v6, v48
	v_mov_b32_e32 v7, v48
	v_mov_b32_e32 v8, v48
	v_mov_b32_e32 v9, v48
	v_mov_b32_e32 v10, v48
	v_mov_b32_e32 v11, v48
	v_mov_b32_e32 v12, v48
	v_mov_b32_e32 v13, v48
	v_mov_b32_e32 v14, v48
	v_mov_b32_e32 v15, v48
	s_barrier

; #define LANDED() do { asm volatile("s_waitcnt vmcnt(0)" ::: "memory"); __syncthreads(); } while (0)
; __device__ __forceinline__ void qkt(f32x16& p0, f32x16& p1, const char* Ks, const bf16x8* qr, int r32, int hi, int mapB) {
;   p0 = f32x16{}; p1 = f32x16{};
; #pragma unroll
;   for (int d0 = 0; d0 < 4; ++d0) { const int cb = (d0 * 16 + hi * 8) * 2 + mapB;
;     bf16x8 b0 = *reinterpret_cast<const bf16x8*>(Ks + KSWZ(r32, cb));
;     bf16x8 b1 = *reinterpret_cast<const bf16x8*>(Ks + KSWZ(32 + r32, cb));
;     p0 = __builtin_amdgcn_mfma_f32_32x32x16_bf16(b0, qr[d0], p0, 0, 0, 0);
;     p1 = __builtin_amdgcn_mfma_f32_32x32x16_bf16(b1, qr[d0], p1, 0, 0, 0); }
; }
; template <bool SH> __device__ __forceinline__ void attn_unit(bf16_t* __restrict__ proj, int tok0, int kv0, int seq, int h, float lam, float oscale, const float* __restrict__ subg, char* lds, bool dry) {
;     ...
;   DMA(0, 0); LANDED();
;   DMA(1, 1);
;   if (ty == 0) {
;     qkt(pA0, pA1, KBUF(0), qr, r32, hi, mapB); partialSM<SH>(pA0, pA1, m_reg, mnA, alA);
;     LANDED();
.LBB0_357:
	s_and_b64 vcc, exec, s[12:13]
	s_cbranch_vccz .LBB0_361
	s_nop 4
	v_and_b32_e32 v16, 0xf0, v210
	v_bitop3_b32 v148, v252, v209, v16 bitop3:0xde
	s_nop 2
	v_add_u32_e32 v4, 0, v148
	ds_read_b128 v[0:3], v4
	ds_read_b128 v[4:7], v4 offset:8192
	v_or_b32_e32 v12, 64, v252
	v_bitop3_b32 v146, v12, v209, v16 bitop3:0xde
	v_add_u32_e32 v12, 0, v146
	s_movk_i32 s8, 0xf0
	v_or_b32_e32 v17, 0x60, v252
	v_bitop3_b32 v149, v252, v210, s8 bitop3:0x78
	s_movk_i32 s8, 0x60
	s_waitcnt lgkmcnt(1)
	v_mfma_f32_32x32x16_bf16 v[64:79], v[0:3], v[140:143], 0
	v_or_b32_e32 v0, 32, v252
	v_bitop3_b32 v147, v0, v209, v16 bitop3:0xde
	v_add_u32_e32 v8, 0, v147
	ds_read_b128 v[0:3], v8
	ds_read_b128 v[8:11], v8 offset:8192
	v_bitop3_b32 v145, v17, v209, v16 bitop3:0xde
	v_bitop3_b32 v150, v252, v16, 32 bitop3:0x36
	v_bitop3_b32 v151, v252, v16, 64 bitop3:0x36
	s_waitcnt lgkmcnt(2)
	v_mfma_f32_32x32x16_bf16 v[80:95], v[4:7], v[140:143], 0
	ds_read_b128 v[4:7], v12
	ds_read_b128 v[12:15], v12 offset:8192
	v_bitop3_b32 v152, v252, v16, s8 bitop3:0x36
	v_add_u32_e32 v16, 0, v145
	s_add_u32 s6, s80, s6
	s_addc_u32 s7, 0, s7
	v_readlane_b32 s8, v255, 10
	s_add_u32 s6, s8, s6
	s_waitcnt lgkmcnt(3)
	v_mfma_f32_32x32x16_bf16 v[64:79], v[0:3], v[136:139], v[64:79]
	ds_read_b128 v[0:3], v16
	ds_read_b128 v[16:19], v16 offset:8192
	v_readlane_b32 s8, v255, 12
	v_mov_b32_e32 v144, 0
	s_addc_u32 s7, s8, s7
	s_mov_b32 s9, 0x10000
	s_mov_b32 s8, 2
	s_waitcnt lgkmcnt(4)
	v_mfma_f32_32x32x16_bf16 v[80:95], v[8:11], v[136:139], v[80:95]
	v_mov_b32_e32 v48, 0
	v_mov_b32_e32 v49, v144
	v_mov_b32_e32 v50, v144
	v_mov_b32_e32 v51, v144
	v_mov_b32_e32 v52, v144
	v_mov_b32_e32 v53, v144
	v_mov_b32_e32 v54, v144
	s_waitcnt lgkmcnt(3)
	v_mfma_f32_32x32x16_bf16 v[64:79], v[4:7], v[132:135], v[64:79]
	v_mov_b32_e32 v55, v144
	v_mov_b32_e32 v56, v144
	v_mov_b32_e32 v57, v144
	v_mov_b32_e32 v58, v144
	v_mov_b32_e32 v59, v144
	v_mov_b32_e32 v60, v144
	v_mov_b32_e32 v61, v144
	s_waitcnt lgkmcnt(2)
	v_mfma_f32_32x32x16_bf16 v[80:95], v[12:15], v[132:135], v[80:95]
	v_mov_b32_e32 v62, v144
	v_mov_b32_e32 v63, v144
	v_mov_b32_e32 v32, 0
	v_mov_b32_e32 v33, v144
	v_mov_b32_e32 v34, v144
	v_mov_b32_e32 v35, v144
	v_mov_b32_e32 v36, v144
	s_waitcnt lgkmcnt(1)
	v_mfma_f32_32x32x16_bf16 v[64:79], v[0:3], v[128:131], v[64:79]
	v_mov_b32_e32 v37, v144
	v_mov_b32_e32 v38, v144
	v_mov_b32_e32 v39, v144
	v_mov_b32_e32 v40, v144
	v_mov_b32_e32 v41, v144
	v_mov_b32_e32 v42, v144
	v_mov_b32_e32 v43, v144
	s_waitcnt lgkmcnt(0)
	v_mfma_f32_32x32x16_bf16 v[80:95], v[16:19], v[128:131], v[80:95]
	v_mov_b32_e32 v44, v144
	v_mov_b32_e32 v45, v144
	v_mov_b32_e32 v46, v144
	v_mov_b32_e32 v47, v144
	v_mov_b32_e32 v16, 0
	v_mov_b32_e32 v17, v144
	v_mov_b32_e32 v18, v144
	v_mov_b32_e32 v19, v144
	v_mov_b32_e32 v20, v144
	v_mov_b32_e32 v21, v144
	v_mov_b32_e32 v22, v144
	v_mov_b32_e32 v23, v144
	v_mov_b32_e32 v24, v144
	v_mov_b32_e32 v25, v144
	v_mov_b32_e32 v26, v144
	v_mov_b32_e32 v27, v144
	v_mov_b32_e32 v28, v144
	v_mov_b32_e32 v29, v144
	v_mov_b32_e32 v30, v144
	v_mov_b32_e32 v31, v144
	v_mov_b32_e32 v0, 0
	v_mov_b32_e32 v1, v144
	v_mov_b32_e32 v2, v144
	v_mov_b32_e32 v3, v144
	v_mov_b32_e32 v4, v144
	v_mov_b32_e32 v5, v144
	v_mov_b32_e32 v6, v144
	v_mov_b32_e32 v7, v144
	v_mov_b32_e32 v8, v144
	v_mov_b32_e32 v9, v144
	v_mov_b32_e32 v10, v144
	v_mov_b32_e32 v11, v144
	v_mov_b32_e32 v12, v144
	v_mov_b32_e32 v13, v144
	v_mov_b32_e32 v14, v144
	v_mov_b32_e32 v15, v144
	s_waitcnt vmcnt(0)
	s_barrier
